# row-per-wave phases: global wave index = wave*gridDim + block, so the fifth pass (context rows) is spread over waves 0-3 of every workgroup instead of all waves of workgroups 0-127
# speedup vs baseline: 1.0225x; 1.0117x over previous
; __global__ void __launch_bounds__(512, 2) mk_fwd(Params Pkarg) {
;     ...
;     for (int ph = ph_lo; ph < ph_hi; ++ph) {
;         asm volatile("" : "+s"(kp));
;     ...
;         const Params P = *kp;
;     ...
;         const Params P = Pkarg;
;     ...
;         unsigned char* ws = P.ws;
;     ...
;         const int kk_ = ph < 2 ? 100 + ph : (ph - 2) % 12;
;         const int nrep_ = (kk_ == PROBE_DUP || kk_ == PROBE_DUP2) ? 2 : 1;
;         for (int rep_ = 0; rep_ < nrep_; ++rep_) { if (rep_) cg::this_grid().sync();
;     ...
;         if (ph == 0) prologue_phase(P, L);
;         else if (ph == 1) rowwise_phase(P, MALL, true, 0, 0, 0, 0.f, false, 0, 0, 0, 1);
;         else {
;             const int q = ph - 2, l = q / 12, k = q % 12;
;             const int Mg = (l == 1 && k >= 6) ? MLAT : MALL;
.LBB0_11:
	s_load_dwordx16 s[4:19], s[82:83], 0x0
	s_load_dwordx4 s[92:95], s[82:83], 0xe0
	s_cmp_lg_u32 s36, 0
	s_cselect_b64 s[0:1], -1, 0
	s_movk_i32 s3, 0x2000
	s_waitcnt lgkmcnt(0)
	v_writelane_b32 v254, s4, 20
	s_nop 1
	v_writelane_b32 v254, s5, 21
	v_writelane_b32 v254, s6, 22
	v_writelane_b32 v254, s7, 23
	v_writelane_b32 v254, s8, 24
	v_writelane_b32 v254, s9, 25
	v_writelane_b32 v254, s10, 26
	v_writelane_b32 v254, s11, 27
	v_writelane_b32 v254, s12, 28
	v_writelane_b32 v254, s13, 29
	v_writelane_b32 v254, s14, 30
	v_writelane_b32 v254, s15, 31
	v_writelane_b32 v254, s16, 32
	v_writelane_b32 v254, s17, 33
	v_writelane_b32 v254, s18, 34
	v_writelane_b32 v254, s19, 35
	s_load_dwordx16 s[4:19], s[82:83], 0x40
	s_waitcnt lgkmcnt(0)
	v_writelane_b32 v254, s4, 36
	s_nop 1
	v_writelane_b32 v254, s5, 37
	v_writelane_b32 v254, s6, 38
	v_writelane_b32 v254, s7, 39
	v_writelane_b32 v254, s8, 40
	v_writelane_b32 v254, s9, 41
	v_writelane_b32 v254, s10, 42
	v_writelane_b32 v254, s11, 43
	v_writelane_b32 v254, s12, 44
	v_writelane_b32 v254, s13, 45
	v_writelane_b32 v254, s14, 46
	v_writelane_b32 v254, s15, 47
	v_writelane_b32 v254, s16, 48
	v_writelane_b32 v254, s17, 49
	v_writelane_b32 v254, s18, 50
	v_writelane_b32 v254, s19, 51
	v_writelane_b32 v254, s0, 52
	s_and_b64 vcc, exec, s[0:1]
	s_nop 0
	v_writelane_b32 v254, s1, 53
	s_mov_b64 s[0:1], -1
	s_cbranch_vccz .LBB0_366
	s_cmp_lg_u32 s36, 1
	s_cbranch_scc0 .LBB0_361
	s_load_dwordx8 s[4:11], s[82:83], 0xc0
	s_add_i32 s0, s36, -2
	s_mul_hi_i32 s1, s0, 0x2aaaaaab
	s_mov_b64 s[56:57], 0
	s_waitcnt lgkmcnt(0)
	v_writelane_b32 v254, s4, 54
	s_nop 1
	v_writelane_b32 v254, s5, 55
	v_writelane_b32 v254, s6, 56
	v_writelane_b32 v254, s7, 57
	v_writelane_b32 v254, s8, 58
	v_writelane_b32 v254, s9, 59
	v_writelane_b32 v254, s10, 60
	v_writelane_b32 v254, s11, 61
	s_load_dwordx16 s[4:19], s[82:83], 0x80
	s_waitcnt lgkmcnt(0)
	v_writelane_b32 v254, s4, 62
	s_nop 1
	v_writelane_b32 v255, s6, 0
	v_writelane_b32 v255, s7, 1
	v_writelane_b32 v255, s8, 2
	v_writelane_b32 v255, s9, 3
	v_writelane_b32 v255, s10, 4
	v_writelane_b32 v255, s11, 5
	v_writelane_b32 v255, s12, 6
	v_writelane_b32 v255, s13, 7
	v_writelane_b32 v255, s14, 8
	v_writelane_b32 v255, s15, 9
	v_writelane_b32 v255, s16, 10
	v_writelane_b32 v255, s17, 11
	v_writelane_b32 v255, s18, 12
	v_writelane_b32 v255, s19, 13
	s_lshr_b32 s4, s1, 31
	s_ashr_i32 s1, s1, 1
	s_add_i32 s6, s1, s4
	s_mov_b32 s4, s6
	v_writelane_b32 v254, s5, 63
	v_writelane_b32 v255, s4, 14
	s_mul_i32 s1, s6, 12
	s_mov_b64 s[10:11], 0
	v_writelane_b32 v255, s5, 15
	s_sub_i32 s4, s0, s1
	v_writelane_b32 v255, s36, 16
	s_add_i32 s0, s36, -14
	s_cmp_lt_u32 s0, 12
	s_cselect_b64 s[8:9], -1, 0
	s_cmp_gt_u32 s0, 11
	v_writelane_b32 v255, s37, 17
	s_cselect_b64 s[6:7], -1, 0
	s_cmp_gt_i32 s4, 5
	s_cselect_b64 s[0:1], -1, 0
	v_writelane_b32 v255, s8, 18
	s_and_b64 s[0:1], s[8:9], s[0:1]
	s_nop 0
	v_writelane_b32 v255, s9, 19
	v_writelane_b32 v255, s0, 20
	s_mov_b64 s[8:9], -1
	s_nop 0
	v_writelane_b32 v255, s1, 21
	s_and_b64 s[0:1], s[0:1], exec
	s_cselect_b32 s0, s3, 0x2400
	v_writelane_b32 v255, s0, 22
	v_writelane_b32 v255, s4, 23
	v_writelane_b32 v255, s10, 24
	s_cmp_lt_i32 s4, 5
	s_nop 0
	v_writelane_b32 v255, s11, 25
	s_mov_b64 s[10:11], 0
	v_writelane_b32 v255, s10, 26
	s_nop 1
	v_writelane_b32 v255, s11, 27
	s_mov_b64 s[10:11], 0
	v_writelane_b32 v255, s10, 28
	s_nop 1
	v_writelane_b32 v255, s11, 29
	s_cbranch_scc1 .LBB0_211
	s_mov_b64 s[4:5], 0
	v_writelane_b32 v255, s4, 26
	s_mov_b64 s[0:1], -1
	s_mov_b64 s[8:9], 0
	v_writelane_b32 v255, s5, 27
	s_mov_b64 s[4:5], 0
	v_readlane_b32 s3, v255, 23
	v_writelane_b32 v255, s4, 24
	s_cmp_gt_i32 s3, 8
	s_nop 0
	v_writelane_b32 v255, s5, 25
	s_cbranch_scc0 .LBB0_31
; __device__ __forceinline__ int tid_() { int t = threadIdx.x; asm volatile("" : "+v"(t)); return t; }
; __device__ __forceinline__ int bid_() { int t = blockIdx.x; asm volatile("" : "+s"(t)); return t; }
; __device__ __forceinline__ void rowwise_phase(const Params& P, int mrows, bool first, int l_post, int j_post, int gate_idx, float coef, bool final_, int l_pre, int j_pre, int shift_idx, int scale_idx) {
;     const int tid = tid_(), lane = tid & 63, wave = __builtin_amdgcn_readfirstlane(tid >> 6);
;     const int gw = bid_() * 8 + wave, NGW = gridDim.x * 8;
;     const float* MOD = (const float*)(P.ws + WS_MOD);
;     float* X = (float*)(P.ws + WS_X); const float* Y = (const float*)(P.ws + WS_Y); bf16* H = (bf16*)(P.ws + WS_H);
;     for (int row = gw; row < mrows; row += NGW) {
; __global__ void __launch_bounds__(512, 2) mk_fwd(Params Pkarg) {
;     ...
;             } else if (k == 2) rowwise_phase(P, MALL, false, l, 0, 2, 0.5f, false, l, 1, 3, 4);
;             else if (k == 8) rowwise_phase(P, Mg, false, l, 1, 5, 1.0f, false, l, 2, 6, 7);
;             else if (k == 11) rowwise_phase(P, Mg, false, l, 2, 8, 0.5f, l == 1, l + 1, 0, 0, 1);
	s_mov_b64 s[4:5], -1
	v_writelane_b32 v255, s4, 24
	s_mov_b64 s[0:1], 0
	s_nop 0
	v_writelane_b32 v255, s5, 25
	s_nop 0
	v_readlane_b32 s3, v255, 23
	s_cmp_gt_i32 s3, 9
	s_cbranch_scc0 .LBB0_31
	s_mov_b64 s[4:5], 0
	v_writelane_b32 v255, s4, 24
	s_mov_b64 s[8:9], -1
	s_nop 0
	v_writelane_b32 v255, s5, 25
	s_nop 0
	v_readlane_b32 s3, v255, 23
	s_cmp_gt_i32 s3, 10
	s_cbranch_scc0 .LBB0_31
	v_readlane_b32 s3, v255, 23
	s_cmp_eq_u32 s3, 11
	s_mov_b64 s[56:57], -1
	s_cbranch_scc0 .LBB0_30
	v_mov_b32_e32 v4, v168
	s_mov_b32 s5, s2
	v_readlane_b32 s98, v254, 18
	v_readlane_b32 s99, v254, 19
	v_readfirstlane_b32 s4, v4
	s_load_dword s98, s[98:99], 0x0
	s_lshl_b32 s5, s5, 3
	s_ashr_i32 s4, s4, 6
	s_waitcnt lgkmcnt(0)
	s_mul_i32 s4, s4, s98
	s_add_i32 s4, s4, s2
	v_readlane_b32 s3, v255, 22
	s_cmp_ge_i32 s4, s3
	s_cbranch_scc1 .LBB0_29
	v_readlane_b32 s8, v254, 18
	v_readlane_b32 s9, v254, 19
	s_load_dword s5, s[8:9], 0x0
	v_readlane_b32 s8, v255, 14
	s_mul_i32 s10, s8, 3
	s_load_dwordx16 s[36:51], s[82:83], 0x0
	v_readlane_b32 s9, v255, 15
	s_waitcnt lgkmcnt(0)
	s_lshl_b32 s8, s5, 3
	s_add_u32 s18, s94, 0x100000
	s_addc_u32 s19, s95, 0
	s_ashr_i32 s11, s10, 31
	s_lshl_b64 s[12:13], s[10:11], 13
	s_add_u32 s20, s94, 0x110000
	s_addc_u32 s21, s95, 0
	s_add_i32 s10, s10, 3
	s_ashr_i32 s11, s10, 31
	s_lshl_b64 s[10:11], s[10:11], 13
	s_add_u32 s5, s50, s12
	v_cmp_lt_i32_e32 vcc, v176, v175
	v_lshlrev_b32_e32 v0, 2, v4
	s_addc_u32 s9, s51, s13
	v_cndmask_b32_e32 v1, v174, v176, vcc
	v_cmp_lt_i32_e32 vcc, v177, v175
	v_and_b32_e32 v0, 0xfc, v0
	s_add_u32 s12, s5, 0x4000
	v_cndmask_b32_e32 v5, v174, v177, vcc
	v_cmp_lt_i32_e32 vcc, v178, v175
	v_or_b32_e32 v12, 0x400, v0
	v_or_b32_e32 v14, 0x500, v0
	v_or_b32_e32 v16, 0x600, v0
	v_or_b32_e32 v18, 0x700, v0
	s_addc_u32 s13, s9, 0
	v_lshlrev_b32_e32 v130, 2, v5
	v_cndmask_b32_e32 v5, v174, v178, vcc
	v_cmp_lt_i32_e32 vcc, v179, v175
	v_lshlrev_b32_e32 v2, 2, v0
	v_lshlrev_b32_e32 v20, 2, v12
	v_mov_b32_e32 v21, v3
	v_lshlrev_b32_e32 v22, 2, v14
	v_mov_b32_e32 v23, v3
	v_lshlrev_b32_e32 v24, 2, v16
	v_mov_b32_e32 v25, v3
	v_lshlrev_b32_e32 v26, 2, v18
	v_mov_b32_e32 v27, v3
	v_lshlrev_b32_e32 v131, 2, v5
	v_cndmask_b32_e32 v5, v174, v179, vcc
	v_cmp_lt_i32_e32 vcc, v180, v175
	v_lshlrev_b32_e32 v28, 1, v0
	v_mov_b32_e32 v29, v3
	s_add_u32 s10, s48, s10
	v_lshl_add_u64 v[92:93], s[12:13], 0, v[2:3]
	v_lshl_add_u64 v[94:95], s[12:13], 0, v[20:21]
	v_lshl_add_u64 v[96:97], s[12:13], 0, v[22:23]
	v_lshl_add_u64 v[98:99], s[12:13], 0, v[24:25]
	v_lshl_add_u64 v[100:101], s[12:13], 0, v[26:27]
	v_lshlrev_b32_e32 v135, 2, v5
	v_cndmask_b32_e32 v5, v174, v180, vcc
	v_cmp_lt_i32_e32 vcc, v181, v175
	v_lshl_add_u64 v[28:29], s[94:95], 0, v[28:29]
	s_mov_b64 s[12:13], 0x34f00000
	s_addc_u32 s11, s49, s11
	s_ashr_i32 s5, s4, 31
	v_or_b32_e32 v6, 0x100, v0
	v_or_b32_e32 v8, 0x200, v0
	v_or_b32_e32 v10, 0x300, v0
	v_lshlrev_b32_e32 v136, 2, v5
	v_cndmask_b32_e32 v5, v174, v181, vcc
	v_lshl_add_u64 v[102:103], v[28:29], 0, s[12:13]
	v_lshl_add_u64 v[104:105], s[10:11], 0, v[2:3]
	v_lshl_add_u64 v[106:107], s[10:11], 0, v[20:21]
	v_lshl_add_u64 v[108:109], s[10:11], 0, v[22:23]
	s_waitcnt vmcnt(0)
	v_lshl_add_u64 v[110:111], s[10:11], 0, v[24:25]
	v_lshl_add_u64 v[112:113], s[10:11], 0, v[26:27]
	s_lshl_b64 s[10:11], s[4:5], 12
	v_and_b32_e32 v2, 63, v4
	s_ashr_i32 s9, s8, 31
	s_lshl_b64 s[12:13], s[4:5], 13
	v_lshlrev_b32_e32 v1, 2, v1
	v_lshlrev_b32_e32 v137, 2, v5
	v_lshl_or_b32 v114, v2, 3, s10
	v_mov_b32_e32 v115, s11
	s_lshl_b64 s[10:11], s[8:9], 12
	v_lshl_or_b32 v116, v2, 4, s12
	v_mov_b32_e32 v117, s13
	s_lshl_b64 s[12:13], s[8:9], 13
	v_lshlrev_b32_e32 v138, 2, v12
	v_lshlrev_b32_e32 v139, 2, v14
	v_lshlrev_b32_e32 v140, 2, v16
	v_lshlrev_b32_e32 v141, 2, v18
	v_lshlrev_b32_e32 v142, 2, v6
	v_lshlrev_b32_e32 v143, 2, v8
	v_lshlrev_b32_e32 v144, 2, v10
	s_branch .LBB0_21

; __device__ __forceinline__ int tid_() { int t = threadIdx.x; asm volatile("" : "+v"(t)); return t; }
; __device__ __forceinline__ int bid_() { int t = blockIdx.x; asm volatile("" : "+s"(t)); return t; }
; __device__ __forceinline__ void rowwise_phase(const Params& P, int mrows, bool first, int l_post, int j_post, int gate_idx, float coef, bool final_, int l_pre, int j_pre, int shift_idx, int scale_idx) {
;     const int tid = tid_(), lane = tid & 63, wave = __builtin_amdgcn_readfirstlane(tid >> 6);
;     const int gw = bid_() * 8 + wave, NGW = gridDim.x * 8;
;     const float* MOD = (const float*)(P.ws + WS_MOD);
;     float* X = (float*)(P.ws + WS_X); const float* Y = (const float*)(P.ws + WS_Y); bf16* H = (bf16*)(P.ws + WS_H);
;     for (int row = gw; row < mrows; row += NGW) {
; __global__ void __launch_bounds__(512, 2) mk_fwd(Params Pkarg) {
;     ...
;             else if (k == 8) rowwise_phase(P, Mg, false, l, 1, 5, 1.0f, false, l, 2, 6, 7);
.LBB0_31:
	v_writelane_b32 v255, s8, 28
	s_and_b64 vcc, exec, s[0:1]
	s_nop 0
	v_writelane_b32 v255, s9, 29
	s_cbranch_vccz .LBB0_41
	v_readlane_b32 s0, v255, 23
	s_cmp_gt_i32 s0, 6
	s_cbranch_scc0 .LBB0_42
	s_cmp_gt_i32 s0, 7
	s_mov_b64 s[0:1], -1
	s_cbranch_scc0 .LBB0_44
	v_mov_b32_e32 v4, v168
	s_mov_b32 s1, s2
	v_readlane_b32 s98, v254, 18
	v_readlane_b32 s99, v254, 19
	v_readfirstlane_b32 s0, v4
	s_load_dword s98, s[98:99], 0x0
	s_lshl_b32 s1, s1, 3
	s_ashr_i32 s0, s0, 6
	s_waitcnt lgkmcnt(0)
	s_mul_i32 s0, s0, s98
	s_add_i32 s0, s0, s2
	v_readlane_b32 s1, v255, 22
	s_cmp_ge_i32 s0, s1
	s_cbranch_scc1 .LBB0_43
	v_readlane_b32 s4, v254, 18
	v_readlane_b32 s5, v254, 19
	s_load_dword s1, s[4:5], 0x0
	v_readlane_b32 s4, v255, 14
	s_mul_i32 s6, s4, 3
	s_load_dwordx16 s[36:51], s[82:83], 0x0
	v_readlane_b32 s5, v255, 15
	s_waitcnt lgkmcnt(0)
	s_lshl_b32 s4, s1, 3
	s_add_u32 s16, s94, 0x100000
	s_addc_u32 s17, s95, 0
	s_add_u32 s18, s94, 0x10a000
	s_addc_u32 s19, s95, 0
	s_ashr_i32 s7, s6, 31
	s_lshl_b64 s[6:7], s[6:7], 13
	s_add_u32 s1, s50, s6
	s_addc_u32 s5, s51, s7
	s_add_u32 s8, s1, 0x2000
	s_addc_u32 s9, s5, 0
	v_cmp_lt_i32_e32 vcc, v176, v175
	s_add_u32 s1, s48, s6
	v_lshlrev_b32_e32 v0, 2, v4
	v_cndmask_b32_e32 v5, v174, v176, vcc
	v_cmp_lt_i32_e32 vcc, v177, v175
	s_addc_u32 s5, s49, s7
	v_and_b32_e32 v6, 0xfc, v0
	v_lshlrev_b32_e32 v122, 2, v5
	v_cndmask_b32_e32 v5, v174, v177, vcc
	v_cmp_lt_i32_e32 vcc, v178, v175
	s_add_u32 s6, s1, 0x4000
	v_or_b32_e32 v14, 0x400, v6
	v_or_b32_e32 v16, 0x500, v6
	v_or_b32_e32 v18, 0x600, v6
	v_or_b32_e32 v20, 0x700, v6
	v_lshlrev_b32_e32 v2, 2, v6
	v_lshlrev_b32_e32 v123, 2, v5
	v_cndmask_b32_e32 v5, v174, v178, vcc
	v_cmp_lt_i32_e32 vcc, v179, v175
	s_addc_u32 s7, s5, 0
	v_lshl_add_u64 v[0:1], s[8:9], 0, v[2:3]
	v_lshlrev_b32_e32 v22, 2, v14
	v_mov_b32_e32 v23, v3
	v_lshlrev_b32_e32 v24, 2, v16
	v_mov_b32_e32 v25, v3
	v_lshlrev_b32_e32 v26, 2, v18
	v_mov_b32_e32 v27, v3
	v_lshlrev_b32_e32 v28, 2, v20
	v_mov_b32_e32 v29, v3
	v_lshlrev_b32_e32 v124, 2, v5
	v_cndmask_b32_e32 v5, v174, v179, vcc
	v_cmp_lt_i32_e32 vcc, v180, v175
	v_lshl_add_u64 v[96:97], s[6:7], 0, v[2:3]
	v_lshlrev_b32_e32 v2, 1, v6
	v_lshl_add_u64 v[88:89], s[8:9], 0, v[22:23]
	v_lshlrev_b32_e32 v125, 2, v5
	v_cndmask_b32_e32 v5, v174, v180, vcc
	v_cmp_lt_i32_e32 vcc, v181, v175
	v_lshl_add_u64 v[98:99], s[6:7], 0, v[22:23]
	v_lshl_add_u64 v[100:101], s[6:7], 0, v[24:25]
	v_lshl_add_u64 v[102:103], s[6:7], 0, v[26:27]
	v_lshl_add_u64 v[104:105], s[6:7], 0, v[28:29]
	v_lshl_add_u64 v[22:23], s[94:95], 0, v[2:3]
	s_mov_b64 s[6:7], 0x34f00000
	s_ashr_i32 s1, s0, 31
	v_or_b32_e32 v8, 0x100, v6
	v_or_b32_e32 v10, 0x200, v6
	v_or_b32_e32 v12, 0x300, v6
	v_lshl_add_u64 v[90:91], s[8:9], 0, v[24:25]
	v_lshl_add_u64 v[92:93], s[8:9], 0, v[26:27]
	v_lshl_add_u64 v[94:95], s[8:9], 0, v[28:29]
	v_lshlrev_b32_e32 v126, 2, v5
	v_cndmask_b32_e32 v5, v174, v181, vcc
	v_lshl_add_u64 v[106:107], v[22:23], 0, s[6:7]
	s_lshl_b64 s[6:7], s[0:1], 12
	v_and_b32_e32 v2, 63, v4
	s_ashr_i32 s5, s4, 31
	s_lshl_b64 s[8:9], s[0:1], 13
	v_lshlrev_b32_e32 v127, 2, v5
	v_lshl_or_b32 v108, v2, 3, s6
	v_mov_b32_e32 v109, s7
	s_lshl_b64 s[6:7], s[4:5], 12
	v_lshl_or_b32 v110, v2, 4, s8
	s_waitcnt vmcnt(0)
	v_mov_b32_e32 v111, s9
	s_lshl_b64 s[8:9], s[4:5], 13
	v_lshlrev_b32_e32 v128, 2, v6
	v_lshlrev_b32_e32 v129, 2, v14
	v_lshlrev_b32_e32 v130, 2, v16
	v_lshlrev_b32_e32 v131, 2, v18
	v_lshlrev_b32_e32 v135, 2, v20
	v_lshlrev_b32_e32 v136, 2, v8
	v_lshlrev_b32_e32 v137, 2, v10
	v_lshlrev_b32_e32 v138, 2, v12
	s_branch .LBB0_37

; __device__ __forceinline__ int tid_() { int t = threadIdx.x; asm volatile("" : "+v"(t)); return t; }
; __device__ __forceinline__ int bid_() { int t = blockIdx.x; asm volatile("" : "+s"(t)); return t; }
; __device__ __forceinline__ void rowwise_phase(const Params& P, int mrows, bool first, int l_post, int j_post, int gate_idx, float coef, bool final_, int l_pre, int j_pre, int shift_idx, int scale_idx) {
;     const int tid = tid_(), lane = tid & 63, wave = __builtin_amdgcn_readfirstlane(tid >> 6);
;     const int gw = bid_() * 8 + wave, NGW = gridDim.x * 8;
;     const float* MOD = (const float*)(P.ws + WS_MOD);
;     float* X = (float*)(P.ws + WS_X); const float* Y = (const float*)(P.ws + WS_Y); bf16* H = (bf16*)(P.ws + WS_H);
;     for (int row = gw; row < mrows; row += NGW) {
; __global__ void __launch_bounds__(512, 2) mk_fwd(Params Pkarg) {
;     ...
;             } else if (k == 2) rowwise_phase(P, MALL, false, l, 0, 2, 0.5f, false, l, 1, 3, 4);
.LBB0_282:
	v_mov_b32_e32 v4, v168
	s_mov_b32 s7, s2
	v_readlane_b32 s98, v254, 18
	v_readlane_b32 s99, v254, 19
	v_readfirstlane_b32 s6, v4
	s_load_dword s98, s[98:99], 0x0
	s_lshl_b32 s7, s7, 3
	s_ashr_i32 s6, s6, 6
	s_waitcnt lgkmcnt(0)
	s_mul_i32 s6, s6, s98
	s_add_i32 s6, s6, s2
	s_cmpk_gt_i32 s6, 0x23ff
	s_cbranch_scc1 .LBB0_294
	v_readlane_b32 s8, v254, 18
	v_readlane_b32 s9, v254, 19
	s_load_dword s7, s[8:9], 0x0
	v_readlane_b32 s8, v255, 14
	s_mul_i32 s16, s8, 3
	v_readlane_b32 s12, v255, 16
	v_readlane_b32 s13, v255, 17
	s_waitcnt lgkmcnt(0)
	s_lshl_b32 s8, s7, 3
	s_add_u32 s26, s94, 0x100000
	s_addc_u32 s27, s95, 0
	s_add_u32 s10, s94, 0x14e00000
	s_addc_u32 s11, s95, 0
	s_add_i32 s7, s12, 9
	s_cmp_gt_u32 s7, 22
	s_cselect_b64 s[12:13], -1, 0
	s_ashr_i32 s17, s16, 31
	s_lshl_b64 s[16:17], s[16:17], 13
	s_add_u32 s28, s94, 0x104000
	v_readlane_b32 s40, v254, 20
	s_addc_u32 s29, s95, 0
	v_readlane_b32 s54, v254, 34
	v_readlane_b32 s55, v254, 35
	s_add_u32 s18, s54, s16
	v_readlane_b32 s52, v254, 32
	s_addc_u32 s19, s55, s17
	v_readlane_b32 s9, v255, 15
	v_readlane_b32 s53, v254, 33
	s_add_u32 s7, s52, s16
	v_lshlrev_b32_e32 v0, 2, v4
	s_addc_u32 s9, s53, s17
	v_and_b32_e32 v6, 0xfc, v0
	s_add_u32 s16, s7, 0x2000
	v_lshlrev_b32_e32 v2, 2, v6
	v_or_b32_e32 v14, 0x400, v6
	v_or_b32_e32 v16, 0x500, v6
	v_or_b32_e32 v18, 0x600, v6
	v_or_b32_e32 v20, 0x700, v6
	v_cmp_lt_i32_e32 vcc, v176, v175
	s_addc_u32 s17, s9, 0
	v_lshl_add_u64 v[0:1], s[10:11], 0, v[2:3]
	v_lshl_add_u64 v[56:57], s[18:19], 0, v[2:3]
	v_lshlrev_b32_e32 v22, 2, v14
	v_mov_b32_e32 v23, v3
	v_lshlrev_b32_e32 v24, 2, v16
	v_mov_b32_e32 v25, v3
	v_lshlrev_b32_e32 v26, 2, v18
	v_mov_b32_e32 v27, v3
	v_lshlrev_b32_e32 v28, 2, v20
	v_mov_b32_e32 v29, v3
	v_cndmask_b32_e32 v5, v174, v176, vcc
	v_cmp_lt_i32_e32 vcc, v177, v175
	v_lshl_add_u64 v[66:67], s[16:17], 0, v[2:3]
	v_lshlrev_b32_e32 v2, 1, v6
	v_lshl_add_u64 v[58:59], s[18:19], 0, v[22:23]
	v_lshlrev_b32_e32 v100, 2, v5
	v_cndmask_b32_e32 v5, v174, v177, vcc
	v_cmp_lt_i32_e32 vcc, v178, v175
	v_lshl_add_u64 v[68:69], s[16:17], 0, v[22:23]
	v_lshl_add_u64 v[70:71], s[16:17], 0, v[24:25]
	v_lshl_add_u64 v[72:73], s[16:17], 0, v[26:27]
	v_lshl_add_u64 v[74:75], s[16:17], 0, v[28:29]
	v_lshl_add_u64 v[22:23], s[94:95], 0, v[2:3]
	s_mov_b64 s[16:17], 0x34f00000
	v_lshlrev_b32_e32 v101, 2, v5
	v_cndmask_b32_e32 v5, v174, v178, vcc
	v_cmp_lt_i32_e32 vcc, v179, v175
	v_lshl_add_u64 v[76:77], v[22:23], 0, s[16:17]
	s_mov_b64 s[16:17], 0x19600000
	s_ashr_i32 s7, s6, 31
	v_lshlrev_b32_e32 v102, 2, v5
	v_cndmask_b32_e32 v5, v174, v179, vcc
	v_cmp_lt_i32_e32 vcc, v180, v175
	v_lshl_add_u64 v[78:79], v[22:23], 0, s[16:17]
	s_ashr_i32 s9, s8, 31
	s_lshl_b64 s[16:17], s[6:7], 12
	v_lshlrev_b32_e32 v103, 2, v5
	v_cndmask_b32_e32 v5, v174, v180, vcc
	v_cmp_lt_i32_e32 vcc, v181, v175
	v_and_b32_e32 v2, 63, v4
	s_add_u32 s16, s94, s16
	v_lshlrev_b32_e32 v104, 2, v5
	v_cndmask_b32_e32 v5, v174, v181, vcc
	v_lshlrev_b32_e32 v2, 3, v2
	s_addc_u32 s17, s95, s17
	v_or_b32_e32 v8, 0x100, v6
	v_or_b32_e32 v10, 0x200, v6
	v_or_b32_e32 v12, 0x300, v6
	v_lshlrev_b32_e32 v105, 2, v5
	v_lshl_add_u64 v[4:5], s[16:17], 0, v[2:3]
	s_mov_b64 s[16:17], 0x1ba00000
	v_lshl_add_u64 v[60:61], s[18:19], 0, v[24:25]
	v_lshl_add_u64 v[62:63], s[18:19], 0, v[26:27]
	v_lshl_add_u64 v[64:65], s[18:19], 0, v[28:29]
	v_lshl_add_u64 v[80:81], v[4:5], 0, s[16:17]
	s_lshl_b64 s[16:17], s[8:9], 12
	v_lshlrev_b32_e32 v106, 2, v6
	v_lshlrev_b32_e32 v107, 2, v14
	v_lshlrev_b32_e32 v108, 2, v16
	v_lshlrev_b32_e32 v109, 2, v18
	v_lshlrev_b32_e32 v110, 2, v20
	s_waitcnt vmcnt(0)
	v_lshlrev_b32_e32 v111, 2, v8
	v_lshlrev_b32_e32 v112, 2, v10
	v_lshlrev_b32_e32 v113, 2, v12
	v_readlane_b32 s41, v254, 21
	v_readlane_b32 s42, v254, 22
	v_readlane_b32 s43, v254, 23
	v_readlane_b32 s44, v254, 24
	v_readlane_b32 s45, v254, 25
	v_readlane_b32 s46, v254, 26
	v_readlane_b32 s47, v254, 27
	v_readlane_b32 s48, v254, 28
	v_readlane_b32 s49, v254, 29
	v_readlane_b32 s50, v254, 30
	v_readlane_b32 s51, v254, 31
	s_branch .LBB0_285

; __device__ __forceinline__ int tid_() { int t = threadIdx.x; asm volatile("" : "+v"(t)); return t; }
; __device__ __forceinline__ int bid_() { int t = blockIdx.x; asm volatile("" : "+s"(t)); return t; }
; __device__ __forceinline__ void post_phase(const Params& P, int l, int mrows) {
;     const int tid = tid_(), lane = tid & 63, wave = __builtin_amdgcn_readfirstlane(tid >> 6);
;     const int gw = bid_() * 8 + wave, NGW = gridDim.x * 8;
;     const float* U = (const float*)(P.ws + WS_U); const bf16* YD = (const bf16*)(P.ws + WS_YD); bf16* YC = (bf16*)(P.ws + WS_H);
;     for (int row = gw; row < mrows; row += NGW) {
;         const bf16* ug = (const bf16*)(P.ws + WS_UG) + (size_t)row * NUG; bf16* yc = YC + (size_t)row * DM;
.LBB0_338:
	s_andn2_b64 vcc, exec, s[56:57]
	s_brev_b32 s24, 60
	v_readlane_b32 s23, v255, 22
	s_cbranch_vccnz .LBB0_343
	v_mov_b32_e32 v10, v168
	s_mov_b32 s1, s2
	v_readlane_b32 s98, v254, 18
	v_readlane_b32 s99, v254, 19
	v_readfirstlane_b32 s0, v10
	s_load_dword s98, s[98:99], 0x0
	s_lshl_b32 s1, s1, 3
	s_ashr_i32 s0, s0, 6
	s_waitcnt lgkmcnt(0)
	s_mul_i32 s0, s0, s98
	s_add_i32 s0, s0, s2
	s_cmp_ge_i32 s0, s23
	s_mov_b32 s3, 0x800000
	s_mov_b32 s22, 0x19600000
	s_cbranch_scc1 .LBB0_342
	v_readlane_b32 s4, v254, 18
	v_readlane_b32 s5, v254, 19
	s_load_dword s21, s[4:5], 0x0
	v_readlane_b32 s4, v255, 14
	s_mov_b32 s10, s4
	s_mov_b32 s8, s10
	v_readlane_b32 s5, v255, 15
	v_writelane_b32 v255, s8, 14
	s_waitcnt lgkmcnt(0)
	v_readlane_b32 s36, v254, 62
	s_ashr_i32 s11, s10, 31
	v_writelane_b32 v255, s9, 15
	s_lshl_b32 s1, s4, 3
	v_readlane_b32 s40, v255, 2
	v_readlane_b32 s41, v255, 3
	s_lshl_b32 s4, s21, 3
	s_lshl_b64 s[6:7], s[10:11], 11
	s_lshl_b64 s[8:9], s[10:11], 9
	s_mov_b64 s[12:13], s[40:41]
	v_lshlrev_b32_e32 v0, 2, v10
	s_add_u32 s6, s12, s6
	v_and_b32_e32 v2, 0xfc, v0
	v_cmp_lt_i32_e32 vcc, v176, v175
	s_addc_u32 s7, s13, s7
	v_readlane_b32 s12, v254, 54
	v_cndmask_b32_e32 v1, v174, v176, vcc
	v_cmp_lt_i32_e32 vcc, v177, v175
	v_or_b32_e32 v4, 0x100, v2
	v_lshlrev_b32_e32 v2, 2, v2
	v_readlane_b32 s18, v254, 60
	v_readlane_b32 s19, v254, 61
	v_lshlrev_b32_e32 v30, 2, v1
	v_cndmask_b32_e32 v1, v174, v177, vcc
	v_cmp_lt_i32_e32 vcc, v178, v175
	v_lshl_add_u64 v[6:7], s[6:7], 0, v[2:3]
	s_mov_b64 s[6:7], s[18:19]
	v_lshlrev_b32_e32 v31, 2, v1
	v_cndmask_b32_e32 v1, v174, v178, vcc
	v_cmp_lt_i32_e32 vcc, v179, v175
	s_add_u32 s6, s6, s8
	v_lshlrev_b32_e32 v2, 4, v10
	v_lshlrev_b32_e32 v32, 2, v1
	v_cndmask_b32_e32 v1, v174, v179, vcc
	v_cmp_lt_i32_e32 vcc, v180, v175
	v_bfe_u32 v0, v0, 6, 2
	v_lshrrev_b32_e32 v4, 6, v4
	s_addc_u32 s7, s7, s9
	v_and_b32_e32 v2, 0x1f0, v2
	v_lshlrev_b32_e32 v33, 2, v1
	v_cndmask_b32_e32 v1, v174, v180, vcc
	v_cmp_lt_i32_e32 vcc, v181, v175
	v_or_b32_e32 v0, s1, v0
	v_or_b32_e32 v4, s1, v4
	v_lshl_add_u64 v[8:9], s[6:7], 0, v[2:3]
	s_ashr_i32 s1, s0, 31
	s_mul_i32 s6, s0, 0x600
	v_lshlrev_b32_e32 v34, 2, v1
	v_cndmask_b32_e32 v1, v174, v181, vcc
	v_readlane_b32 s38, v255, 0
	v_readlane_b32 s39, v255, 1
	s_mul_hi_i32 s5, s0, 0x600
	s_add_u32 s8, s94, s6
	v_lshlrev_b32_e32 v35, 2, v1
	v_ashrrev_i32_e32 v1, 31, v0
	v_ashrrev_i32_e32 v5, 31, v4
	s_mov_b64 s[10:11], s[38:39]
	s_addc_u32 s9, s95, s5
	s_ashr_i32 s5, s4, 31
	s_lshl_b64 s[6:7], s[0:1], 10
	v_lshl_add_u64 v[0:1], v[0:1], 2, s[10:11]
	v_lshl_add_u64 v[4:5], v[4:5], 2, s[10:11]
	v_readlane_b32 s13, v254, 55
	s_add_u32 s10, s94, s6
	v_readlane_b32 s14, v254, 56
	s_addc_u32 s11, s95, s7
	s_lshl_b64 s[12:13], s[4:5], 10
	s_lshl_b64 s[6:7], s[0:1], 12
	v_readlane_b32 s15, v254, 57
	v_readlane_b32 s16, v254, 58
	v_readlane_b32 s17, v254, 59
	s_add_u32 s14, s94, s6
	s_addc_u32 s15, s95, s7
	s_lshl_b64 s[16:17], s[4:5], 12
	s_mul_i32 s5, s0, 0x2a00
	v_and_b32_e32 v2, 63, v10
	s_mul_hi_i32 s1, s0, 0x2a00
	s_add_u32 s18, s94, s5
	v_lshlrev_b32_e32 v2, 3, v2
	s_mul_i32 s20, s21, 0x3000
	s_addc_u32 s19, s95, s1
	s_mul_i32 s1, s21, 0x15000
	v_readlane_b32 s37, v254, 63
	v_readlane_b32 s42, v255, 4
	v_readlane_b32 s43, v255, 5
	v_readlane_b32 s44, v255, 6
	v_readlane_b32 s45, v255, 7
	v_readlane_b32 s46, v255, 8
	v_readlane_b32 s47, v255, 9
	v_readlane_b32 s48, v255, 10
	v_readlane_b32 s49, v255, 11
	v_readlane_b32 s50, v255, 12
	v_readlane_b32 s51, v255, 13

; __device__ __forceinline__ unsigned pk2(float lo, float hi) { return f2bf(lo) | (f2bf(hi) << 16); }
; __device__ __forceinline__ float dot4(f32x4 a) { return (a.x * a.x + a.y * a.y) + (a.z * a.z + a.w * a.w); }
; __device__ __forceinline__ int tid_() { int t = threadIdx.x; asm volatile("" : "+v"(t)); return t; }
; __device__ __forceinline__ void rowwise_phase(const Params& P, int mrows, bool first, int l_post, int j_post, int gate_idx, float coef, bool final_, int l_pre, int j_pre, int shift_idx, int scale_idx) {
;     const int tid = tid_(), lane = tid & 63, wave = __builtin_amdgcn_readfirstlane(tid >> 6);
;     const int gw = bid_() * 8 + wave, NGW = gridDim.x * 8;
;     const float* MOD = (const float*)(P.ws + WS_MOD);
;     float* X = (float*)(P.ws + WS_X); const float* Y = (const float*)(P.ws + WS_Y); bf16* H = (bf16*)(P.ws + WS_H);
;     for (int row = gw; row < mrows; row += NGW) {
;         const int b = row < MLAT ? (row >> 11) : 4;
;         f32x4 xv[8]; float ss_new = 0.f;
;         if (first) {
;             const float* src = row < MLAT ? P.x + (size_t)row * DM : P.ctx + (size_t)(row - MLAT) * DM;
; #pragma unroll
;             for (int j = 0; j < 8; ++j) xv[j] = *(const f32x4*)(src + 4 * lane + 256 * j);
;     ...
;         {
;             float* xr = X + (size_t)row * DM; float ss = 0.f;
; #pragma unroll
;             for (int j = 0; j < 8; ++j) { if (!first) *(f32x4*)(xr + 4 * lane + 256 * j) = xv[j]; else ss += dot4(xv[j]); }
;             if (first) ss = wave_sum(ss); else ss = ss_new;
;             const float rs = rsqrtf(ss * (1.f / DM) + EPS);
;             const float* gp = P.norm_pre + (size_t)(l_pre * 3 + j_pre) * DM; const float* mb = MOD + (size_t)(l_pre * 5 + b) * NMODV;
;             bf16* hr = H + (size_t)row * DM;
; #pragma unroll
;             for (int j = 0; j < 8; ++j) { const int c = 4 * lane + 256 * j; const f32x4 g4 = *(const f32x4*)(gp + c), sh = *(const f32x4*)(mb + shift_idx * DM + c), scl = *(const f32x4*)(mb + scale_idx * DM + c);
;                 const f32x4 h = (xv[j] * rs) * g4 * (scl + 1.f) + sh; u32x2 w; w.x = pk2(h.x, h.y); w.y = pk2(h.z, h.w); *(u32x2*)(hr + c) = w; }
; __global__ void __launch_bounds__(512, 2) mk_fwd(Params Pkarg) {
;     ...
;         else if (ph == 1) rowwise_phase(P, MALL, true, 0, 0, 0, 0.f, false, 0, 0, 0, 1);
.LBB0_361:
	s_and_b64 vcc, exec, s[0:1]
	s_cbranch_vccz .LBB0_365
	v_mov_b32_e32 v4, v168
	s_mov_b32 s1, s2
	v_readlane_b32 s98, v254, 18
	v_readlane_b32 s99, v254, 19
	v_readfirstlane_b32 s0, v4
	s_load_dword s98, s[98:99], 0x0
	s_lshl_b32 s1, s1, 3
	s_ashr_i32 s0, s0, 6
	s_waitcnt lgkmcnt(0)
	s_mul_i32 s0, s0, s98
	s_add_i32 s0, s0, s2
	s_cmpk_gt_i32 s0, 0x23ff
	s_cbranch_scc1 .LBB0_365
	v_lshlrev_b32_e32 v0, 2, v4
	v_cmp_lt_i32_e32 vcc, v176, v175
	v_and_b32_e32 v6, 0xfc, v0
	s_load_dword s1, s[38:39], 0x0
	v_cndmask_b32_e32 v0, v174, v176, vcc
	v_cmp_lt_i32_e32 vcc, v177, v175
	v_lshlrev_b32_e32 v31, 2, v0
	v_readlane_b32 s40, v254, 20
	v_cndmask_b32_e32 v0, v174, v177, vcc
	v_cmp_lt_i32_e32 vcc, v178, v175
	v_lshlrev_b32_e32 v32, 2, v0
	v_or_b32_e32 v14, 0x400, v6
	v_cndmask_b32_e32 v0, v174, v178, vcc
	v_cmp_lt_i32_e32 vcc, v179, v175
	v_lshlrev_b32_e32 v33, 2, v0
	v_lshlrev_b32_e32 v2, 2, v6
	v_cndmask_b32_e32 v0, v174, v179, vcc
	v_cmp_lt_i32_e32 vcc, v180, v175
	v_lshlrev_b32_e32 v34, 2, v0
	v_readlane_b32 s52, v254, 32
	v_cndmask_b32_e32 v0, v174, v180, vcc
	v_cmp_lt_i32_e32 vcc, v181, v175
	v_lshlrev_b32_e32 v35, 2, v0
	v_readlane_b32 s53, v254, 33
	v_cndmask_b32_e32 v0, v174, v181, vcc
	s_waitcnt lgkmcnt(0)
	s_lshl_b32 s4, s1, 3
	v_or_b32_e32 v16, 0x500, v6
	v_lshlrev_b32_e32 v36, 2, v0
	v_lshl_add_u64 v[0:1], s[52:53], 0, v[2:3]
	v_lshlrev_b32_e32 v2, 2, v14
	s_add_u32 s12, s94, 0x100000
	v_or_b32_e32 v18, 0x600, v6
	v_lshl_add_u64 v[20:21], s[52:53], 0, v[2:3]
	v_lshlrev_b32_e32 v2, 2, v16
	s_addc_u32 s13, s95, 0
	v_or_b32_e32 v30, 0x700, v6
	v_lshl_add_u64 v[22:23], s[52:53], 0, v[2:3]
	v_lshlrev_b32_e32 v2, 2, v18
	s_ashr_i32 s1, s0, 31
	v_lshl_add_u64 v[24:25], s[52:53], 0, v[2:3]
	v_lshlrev_b32_e32 v2, 2, v30
	s_lshl_b64 s[6:7], s[0:1], 12
	v_lshl_add_u64 v[26:27], s[52:53], 0, v[2:3]
	v_and_b32_e32 v2, 63, v4
	s_add_u32 s6, s94, s6
	v_lshlrev_b32_e32 v2, 3, v2
	s_addc_u32 s7, s95, s7
	v_or_b32_e32 v8, 0x100, v6
	v_or_b32_e32 v10, 0x200, v6
	v_or_b32_e32 v12, 0x300, v6
	v_lshl_add_u64 v[4:5], s[6:7], 0, v[2:3]
	s_mov_b64 s[6:7], 0x19600000
	s_ashr_i32 s5, s4, 31
	v_readlane_b32 s41, v254, 21
	v_readlane_b32 s44, v254, 24
	v_readlane_b32 s45, v254, 25
	v_lshl_add_u64 v[28:29], v[4:5], 0, s[6:7]
	s_lshl_b64 s[6:7], s[4:5], 12
	v_lshlrev_b32_e32 v2, 2, v6
	v_lshlrev_b32_e32 v37, 2, v8
	v_lshlrev_b32_e32 v38, 2, v10
	v_lshlrev_b32_e32 v39, 2, v12
	v_lshlrev_b32_e32 v40, 2, v14
	v_lshlrev_b32_e32 v41, 2, v16
	v_lshlrev_b32_e32 v42, 2, v18
	v_lshlrev_b32_e32 v43, 2, v30
	s_mov_b32 s3, 0x800000
	s_movk_i32 s16, 0x1000
	v_readlane_b32 s42, v254, 22
	v_readlane_b32 s43, v254, 23
	v_readlane_b32 s46, v254, 26
	v_readlane_b32 s47, v254, 27
	v_readlane_b32 s48, v254, 28
	v_readlane_b32 s49, v254, 29
	v_readlane_b32 s50, v254, 30
	v_readlane_b32 s51, v254, 31
	v_readlane_b32 s54, v254, 34
	v_readlane_b32 s55, v254, 35
